# dense attention: static priority 2 given to waves 4-7 (the younger half) instead of waves 0-3
# speedup vs baseline: 1.0180x; 1.0180x over previous
.LBB0_380:
	s_andn2_b64 vcc, exec, s[10:11]
	s_cbranch_vccnz .LBB0_563
	s_mov_b64 s[10:11], -1
	s_and_b64 vcc, exec, s[16:17]
	s_cbranch_vccz .LBB0_434
	v_readfirstlane_b32 s10, v206
	s_cmpk_gt_u32 s10, 0xff
	s_cbranch_scc0 .LBB0_384
	s_setprio 2
